# once-read input streams (w_in in P0 transposes, w_ada in adaLN, x in P1) loaded with nt so they do not evict the bf16 intermediates the next GEMM re-reads
# speedup vs baseline: 1.0343x; 1.0278x over previous
; #define LAS __attribute__((address_space(3)))
; __device__ __forceinline__ unsigned pk2(float lo, float hi) { return pk2hw(lo, hi); }
; __device__ __forceinline__ void transpose_item(const float* W, int K, int N, bf16_t* WT, int drow0, LAS float* scr, int k0, int n0, int lane) {
; #pragma unroll 8
;     for (int i = 0; i < 32; ++i) { const int kk = 2 * i + (lane >> 5); scr[kk * 33 + (lane & 31)] = W[(size_t)(k0 + kk) * N + n0 + (lane & 31)]; }
;     asm volatile("s_waitcnt lgkmcnt(0)" ::: "memory");
;     const int c = lane & 7;
; #pragma unroll
;     for (int j = 0; j < 4; ++j) { const int n = (lane >> 3) + 8 * j; const LAS float* s = scr + (8 * c) * 33 + n;
;         u32x4 o; o.x = pk2(s[0 * 33], s[1 * 33]); o.y = pk2(s[2 * 33], s[3 * 33]); o.z = pk2(s[4 * 33], s[5 * 33]); o.w = pk2(s[6 * 33], s[7 * 33]);
;         *(u32x4*)(WT + (size_t)(drow0 + n) * K + k0 + 8 * c) = o; }
;     asm volatile("s_waitcnt lgkmcnt(0)" ::: "memory");
; __global__ void __launch_bounds__(NTHR, 2) fwd_kernel(Args a) {
;     ...
;         for (int it = gw; it < IT_IN; it += NGW) {
;             const int r = it, kb = r / 257, nb = r % 257, n0 = nb * 32; const int d0 = n0 < 3072 ? n0 : (n0 == 3072 ? 8192 : n0 - 32);
;             transpose_item(a.in[I_WIN], DM, INW, WinT, d0, scr, kb * 64, n0, lane);
.LBB0_22:
	s_lshl_b32 s12, s9, 1
	s_lshl_b32 s13, s8, 1
	v_or_b32_e32 v48, s12, v1
	v_or_b32_e32 v49, s13, v0
	s_add_i32 s14, s12, 4
	s_add_i32 s15, s13, 4
	s_add_i32 s16, s12, 8
	s_add_i32 s17, s13, 8
	s_add_i32 s18, s12, 12
	s_add_i32 s19, s13, 12
	s_add_i32 s20, s12, 16
	s_add_i32 s21, s13, 16
	s_add_i32 s22, s12, 20
	s_add_i32 s23, s13, 20
	s_add_i32 s24, s12, 24
	s_add_i32 s25, s13, 24
	s_add_i32 s12, s12, 28
	s_add_i32 s13, s13, 28
	v_add_u32_e32 v16, s0, v49
	v_or_b32_e32 v50, s14, v1
	v_or_b32_e32 v51, s15, v0
	v_or_b32_e32 v52, s16, v1
	v_or_b32_e32 v53, s17, v0
	v_or_b32_e32 v54, s18, v1
	v_or_b32_e32 v55, s19, v0
	v_or_b32_e32 v56, s20, v1
	v_or_b32_e32 v57, s21, v0
	v_or_b32_e32 v58, s22, v1
	v_or_b32_e32 v59, s23, v0
	v_or_b32_e32 v60, s24, v1
	v_or_b32_e32 v61, s25, v0
	v_or_b32_e32 v62, s12, v1
	v_or_b32_e32 v63, s13, v0
	v_add_u32_e32 v18, s3, v48
	v_mad_i64_i32 v[16:17], s[12:13], v16, s6, v[8:9]
	v_add_u32_e32 v22, s3, v50
	v_add_u32_e32 v20, s0, v51
	v_add_u32_e32 v26, s3, v52
	v_add_u32_e32 v24, s0, v53
	v_add_u32_e32 v30, s3, v54
	v_add_u32_e32 v28, s0, v55
	v_add_u32_e32 v34, s3, v56
	v_add_u32_e32 v32, s0, v57
	v_add_u32_e32 v38, s3, v58
	v_add_u32_e32 v36, s0, v59
	v_add_u32_e32 v42, s3, v60
	v_add_u32_e32 v40, s0, v61
	v_add_u32_e32 v46, s3, v62
	v_add_u32_e32 v44, s0, v63
	v_mad_i64_i32 v[18:19], s[12:13], v18, s6, v[8:9]
	v_mad_i64_i32 v[20:21], s[12:13], v20, s6, v[8:9]
	v_mad_i64_i32 v[22:23], s[12:13], v22, s6, v[8:9]
	v_mad_i64_i32 v[24:25], s[12:13], v24, s6, v[8:9]
	v_mad_i64_i32 v[26:27], s[12:13], v26, s6, v[8:9]
	v_mad_i64_i32 v[28:29], s[12:13], v28, s6, v[8:9]
	v_mad_i64_i32 v[30:31], s[12:13], v30, s6, v[8:9]
	v_mad_i64_i32 v[32:33], s[12:13], v32, s6, v[8:9]
	v_mad_i64_i32 v[34:35], s[12:13], v34, s6, v[8:9]
	v_mad_i64_i32 v[36:37], s[12:13], v36, s6, v[8:9]
	v_mad_i64_i32 v[38:39], s[12:13], v38, s6, v[8:9]
	v_mad_i64_i32 v[40:41], s[12:13], v40, s6, v[8:9]
	v_mad_i64_i32 v[42:43], s[12:13], v42, s6, v[8:9]
	v_mad_i64_i32 v[44:45], s[12:13], v44, s6, v[8:9]
	v_mad_i64_i32 v[46:47], s[12:13], v46, s6, v[8:9]
	global_load_dword v64, v[16:17], off nt
	global_load_dword v65, v[18:19], off nt
	global_load_dword v66, v[20:21], off nt
	global_load_dword v67, v[22:23], off nt
	global_load_dword v68, v[24:25], off nt
	global_load_dword v69, v[26:27], off nt
	global_load_dword v70, v[28:29], off nt
	global_load_dword v71, v[30:31], off nt
	global_load_dword v72, v[32:33], off nt
	global_load_dword v73, v[34:35], off nt
	global_load_dword v74, v[36:37], off nt
	global_load_dword v75, v[38:39], off nt
	global_load_dword v76, v[40:41], off nt
	global_load_dword v77, v[42:43], off nt
	global_load_dword v78, v[44:45], off nt
	global_load_dword v79, v[46:47], off nt
	s_add_i32 s8, s8, 16
	s_add_i32 s9, s9, 16
	s_add_i32 s7, s7, -16
	v_mad_u64_u32 v[16:17], s[12:13], v49, s5, v[4:5]
	s_cmp_lg_u32 s7, 0
	v_mad_u64_u32 v[18:19], s[12:13], v48, s5, v[4:5]
	v_mad_u64_u32 v[20:21], s[12:13], v51, s5, v[4:5]
	v_mad_u64_u32 v[22:23], s[12:13], v50, s5, v[4:5]
	v_mad_u64_u32 v[24:25], s[12:13], v53, s5, v[4:5]
	v_mad_u64_u32 v[26:27], s[12:13], v52, s5, v[4:5]
	v_mad_u64_u32 v[28:29], s[12:13], v55, s5, v[4:5]
	v_mad_u64_u32 v[30:31], s[12:13], v54, s5, v[4:5]
	v_mad_u64_u32 v[32:33], s[12:13], v57, s5, v[4:5]
	v_mad_u64_u32 v[34:35], s[12:13], v56, s5, v[4:5]
	v_mad_u64_u32 v[36:37], s[12:13], v59, s5, v[4:5]
	v_mad_u64_u32 v[38:39], s[12:13], v58, s5, v[4:5]
	v_mad_u64_u32 v[40:41], s[12:13], v61, s5, v[4:5]
	v_mad_u64_u32 v[42:43], s[12:13], v60, s5, v[4:5]
	v_mad_u64_u32 v[44:45], s[12:13], v63, s5, v[4:5]
	v_mad_u64_u32 v[46:47], s[12:13], v62, s5, v[4:5]
	s_waitcnt vmcnt(15)
	ds_write_b32 v16, v64
	s_waitcnt vmcnt(14)
	ds_write_b32 v18, v65
	s_waitcnt vmcnt(13)
	ds_write_b32 v20, v66
	s_waitcnt vmcnt(12)
	ds_write_b32 v22, v67
	s_waitcnt vmcnt(11)
	ds_write_b32 v24, v68
	s_waitcnt vmcnt(10)
	ds_write_b32 v26, v69
	s_waitcnt vmcnt(9)
	ds_write_b32 v28, v70
	s_waitcnt vmcnt(8)
	ds_write_b32 v30, v71
	s_waitcnt vmcnt(7)
	ds_write_b32 v32, v72
	s_waitcnt vmcnt(6)
	ds_write_b32 v34, v73
	s_waitcnt vmcnt(5)
	ds_write_b32 v36, v74
	s_waitcnt vmcnt(4)
	ds_write_b32 v38, v75
	s_waitcnt vmcnt(3)
	ds_write_b32 v40, v76
	s_waitcnt vmcnt(2)
	ds_write_b32 v42, v77
	s_waitcnt vmcnt(1)
	ds_write_b32 v44, v78
	s_waitcnt vmcnt(0)
	ds_write_b32 v46, v79
	s_cbranch_scc1 .LBB0_22
	s_sub_i32 s3, s2, 32
	s_cmpk_lg_i32 s1, 0x60
	s_waitcnt lgkmcnt(0)
	s_cselect_b32 s3, s3, 0x2000
	s_cmpk_lt_i32 s1, 0x60
	ds_read2_b32 v[8:9], v12 offset0:33 offset1:41
	ds_read2_b32 v[20:21], v12 offset1:8
	ds_read2_b32 v[22:23], v12 offset0:66 offset1:74
	ds_read2_b32 v[24:25], v12 offset0:99 offset1:107
	ds_read2_b32 v[26:27], v12 offset0:132 offset1:140
	ds_read2_b32 v[28:29], v12 offset0:165 offset1:173
	ds_read2_b32 v[30:31], v12 offset0:198 offset1:206
	ds_read2_b32 v[32:33], v12 offset0:231 offset1:239
	s_cselect_b32 s2, s2, s3
	v_or_b32_e32 v36, s2, v11
	s_ashr_i32 s1, s0, 31
	v_ashrrev_i32_e32 v37, 31, v36
	v_lshl_add_u64 v[34:35], s[0:1], 1, v[6:7]
	v_lshlrev_b64 v[36:37], 12, v[36:37]
	s_waitcnt lgkmcnt(6)
	v_cvt_pk_bf16_f32 v16, v20, v8
	s_waitcnt lgkmcnt(4)
	v_cvt_pk_bf16_f32 v17, v22, v24
	s_waitcnt lgkmcnt(2)
	v_cvt_pk_bf16_f32 v18, v26, v28
	s_waitcnt lgkmcnt(0)
	v_cvt_pk_bf16_f32 v19, v30, v32
	v_lshl_add_u64 v[36:37], v[34:35], 0, v[36:37]
	v_or_b32_e32 v8, s2, v13
	global_store_dwordx4 v[36:37], v[16:19], off sc1
	s_add_i32 s4, s4, s70
	s_cmpk_gt_i32 s4, 0x201f
	v_cvt_pk_bf16_f32 v16, v21, v9
	v_ashrrev_i32_e32 v9, 31, v8
	v_cvt_pk_bf16_f32 v17, v23, v25
	v_cvt_pk_bf16_f32 v18, v27, v29
	v_cvt_pk_bf16_f32 v19, v31, v33
	v_lshlrev_b64 v[8:9], 12, v[8:9]
	ds_read2_b32 v[20:21], v12 offset0:49 offset1:57
	ds_read2_b32 v[22:23], v12 offset0:16 offset1:24
	ds_read2_b32 v[24:25], v12 offset0:82 offset1:90
	ds_read2_b32 v[26:27], v12 offset0:115 offset1:123
	ds_read2_b32 v[28:29], v12 offset0:148 offset1:156
	ds_read2_b32 v[30:31], v12 offset0:181 offset1:189
	ds_read2_b32 v[32:33], v12 offset0:214 offset1:222
	ds_read2_b32 v[36:37], v12 offset0:247 offset1:255
	v_lshl_add_u64 v[8:9], v[34:35], 0, v[8:9]
	global_store_dwordx4 v[8:9], v[16:19], off sc1
	v_or_b32_e32 v8, s2, v14
	v_ashrrev_i32_e32 v9, 31, v8
	v_lshlrev_b64 v[8:9], 12, v[8:9]
	s_waitcnt lgkmcnt(6)
	v_cvt_pk_bf16_f32 v16, v22, v20
	s_waitcnt lgkmcnt(4)
	v_cvt_pk_bf16_f32 v17, v24, v26
	s_waitcnt lgkmcnt(2)
	v_cvt_pk_bf16_f32 v18, v28, v30
	s_waitcnt lgkmcnt(0)
	v_cvt_pk_bf16_f32 v19, v32, v36
	v_lshl_add_u64 v[8:9], v[34:35], 0, v[8:9]
	global_store_dwordx4 v[8:9], v[16:19], off sc1
	v_or_b32_e32 v8, s2, v15
	v_ashrrev_i32_e32 v9, 31, v8
	v_lshlrev_b64 v[8:9], 12, v[8:9]
	v_cvt_pk_bf16_f32 v16, v23, v21
	v_cvt_pk_bf16_f32 v17, v25, v27
	v_cvt_pk_bf16_f32 v18, v29, v31
	v_cvt_pk_bf16_f32 v19, v33, v37
	v_lshl_add_u64 v[8:9], v[34:35], 0, v[8:9]
	global_store_dwordx4 v[8:9], v[16:19], off sc1
	s_waitcnt lgkmcnt(0)
	s_cbranch_scc0 .LBB0_21

; __global__ void __launch_bounds__(NTHR, 2) fwd_kernel(Args a) {
;     ...
;         for (int cb = bx; cb < 256; cb += G) {
;             const int col = cb * 48 + (lane < 48 ? lane : 47);
;             float acc[5] = {0.f, 0.f, 0.f, 0.f, 0.f};
;             const float* wp = a.in[I_WADA] + (size_t)(wave * 256) * MODW + col;
; #pragma unroll 16
;             for (int kk = 0; kk < 256; ++kk) {
;                 const float w = wp[(size_t)kk * MODW];
; #pragma unroll
;                 for (int r = 0; r < 5; ++r) acc[r] += w * sl[r * DM + wave * 256 + kk];
.LBB0_104:
	v_lshl_add_u64 v[10:11], v[4:5], 0, s[12:13]
	v_add_co_u32_e64 v96, s[4:5], s14, v10
	global_load_dword v94, v[10:11], off nt
	s_nop 0
	v_addc_co_u32_e64 v97, s[4:5], 0, v11, s[4:5]
	v_add_co_u32_e64 v98, s[4:5], s17, v10
	v_mov_b32_e32 v90, s33
	s_nop 0
	v_addc_co_u32_e64 v99, s[4:5], 0, v11, s[4:5]
	v_add_co_u32_e64 v100, s[4:5], s18, v10
	ds_read_b128 v[14:17], v90
	ds_read_b128 v[18:21], v90 offset:16
	v_addc_co_u32_e64 v101, s[4:5], 0, v11, s[4:5]
	v_add_co_u32_e64 v102, s[4:5], s19, v10
	ds_read_b128 v[22:25], v90 offset:8192
	ds_read_b128 v[26:29], v90 offset:8208
	ds_read_b128 v[30:33], v90 offset:16384
	ds_read_b128 v[34:37], v90 offset:16400
	ds_read_b128 v[38:41], v90 offset:24576
	ds_read_b128 v[42:45], v90 offset:24592
	ds_read_b128 v[46:49], v90 offset:32768
	ds_read_b128 v[50:53], v90 offset:32784
	v_addc_co_u32_e64 v103, s[4:5], 0, v11, s[4:5]
	v_add_co_u32_e64 v104, s[4:5], s20, v10
	ds_read_b128 v[54:57], v90 offset:32
	ds_read_b128 v[58:61], v90 offset:48
	v_addc_co_u32_e64 v105, s[4:5], 0, v11, s[4:5]
	v_add_co_u32_e64 v106, s[4:5], s21, v10
	ds_read_b128 v[62:65], v90 offset:8224
	ds_read_b128 v[66:69], v90 offset:8240
	ds_read_b128 v[70:73], v90 offset:16416
	ds_read_b128 v[74:77], v90 offset:16432
	ds_read_b128 v[78:81], v90 offset:24608
	ds_read_b128 v[82:85], v90 offset:24624
	ds_read_b128 v[86:89], v90 offset:32800
	ds_read_b128 v[90:93], v90 offset:32816
	v_addc_co_u32_e64 v107, s[4:5], 0, v11, s[4:5]
	v_add_co_u32_e64 v108, s[4:5], s22, v10
	s_waitcnt lgkmcnt(14)
	v_mov_b32_e32 v124, v30
	v_addc_co_u32_e64 v109, s[4:5], 0, v11, s[4:5]
	v_add_co_u32_e64 v110, s[4:5], s23, v10
	v_mov_b32_e32 v125, v22
	s_nop 0
	v_addc_co_u32_e64 v111, s[4:5], 0, v11, s[4:5]
	v_add_co_u32_e64 v112, s[4:5], s24, v10
	v_mov_b32_e32 v22, v31
	s_nop 0
	v_addc_co_u32_e64 v113, s[4:5], 0, v11, s[4:5]
	v_add_co_u32_e64 v114, s[4:5], s25, v10
	v_mov_b32_e32 v30, v32
	s_nop 0
	v_addc_co_u32_e64 v115, s[4:5], 0, v11, s[4:5]
	v_add_co_u32_e64 v116, s[4:5], s26, v10
	v_mov_b32_e32 v31, v24
	s_nop 0
	v_addc_co_u32_e64 v117, s[4:5], 0, v11, s[4:5]
	v_add_co_u32_e64 v118, s[4:5], s27, v10
	v_mov_b32_e32 v24, v33
	s_nop 0
	v_addc_co_u32_e64 v119, s[4:5], 0, v11, s[4:5]
	v_add_co_u32_e64 v120, s[4:5], s28, v10
	s_waitcnt lgkmcnt(11)
	v_mov_b32_e32 v32, v46
	v_addc_co_u32_e64 v121, s[4:5], 0, v11, s[4:5]
	v_add_co_u32_e64 v122, s[4:5], s29, v10
	v_mov_b32_e32 v33, v38
	s_nop 0
	v_addc_co_u32_e64 v123, s[4:5], 0, v11, s[4:5]
	v_add_co_u32_e64 v10, s[4:5], s30, v10
	v_mov_b32_e32 v38, v47
	s_nop 0
	v_addc_co_u32_e64 v11, s[4:5], 0, v11, s[4:5]
	global_load_dword v96, v[96:97], off nt
	s_nop 0
	global_load_dword v98, v[98:99], off nt
	s_nop 0
	global_load_dword v100, v[100:101], off nt
	s_nop 0
	global_load_dword v102, v[102:103], off nt
	s_nop 0
	global_load_dword v104, v[104:105], off nt
	s_nop 0
	global_load_dword v106, v[106:107], off nt
	s_nop 0
	global_load_dword v108, v[108:109], off nt
	s_nop 0
	global_load_dword v110, v[110:111], off nt
	s_nop 0
	global_load_dword v112, v[112:113], off nt
	s_nop 0
	global_load_dword v114, v[114:115], off nt
	s_nop 0
	global_load_dword v116, v[116:117], off nt
	s_nop 0
	global_load_dword v118, v[118:119], off nt
	s_nop 0
	global_load_dword v120, v[120:121], off nt
	s_nop 0
	global_load_dword v122, v[122:123], off nt
	s_nop 0
	global_load_dword v10, v[10:11], off nt
	v_mov_b32_e32 v46, v48
	v_mov_b32_e32 v47, v40
	v_mov_b32_e32 v40, v49
	v_mov_b32_e32 v48, v34
	v_mov_b32_e32 v49, v26
	v_mov_b32_e32 v26, v35
	s_waitcnt vmcnt(15)
	v_pk_fma_f32 v[8:9], v[94:95], v[124:125], v[8:9] op_sel_hi:[0,1,1]
	v_pk_fma_f32 v[6:7], v[94:95], v[32:33], v[6:7] op_sel_hi:[0,1,1]
	v_fmac_f32_e32 v3, v94, v14
	v_mov_b32_e32 v34, v36
	v_mov_b32_e32 v35, v28
	v_mov_b32_e32 v28, v37
	s_waitcnt lgkmcnt(10)
; __global__ void __launch_bounds__(NTHR, 2) fwd_kernel(Args a) {
;     ...
;             for (int kk = 0; kk < 256; ++kk) {
;                 const float w = wp[(size_t)kk * MODW];
; #pragma unroll
;                 for (int r = 0; r < 5; ++r) acc[r] += w * sl[r * DM + wave * 256 + kk];
;             }
;             if (lane < 48) {
; #pragma unroll
;                 for (int r = 0; r < 5; ++r) red[(wave * 5 + r) * 48 + lane] = acc[r];
;             }
	v_mov_b32_e32 v36, v50
	v_mov_b32_e32 v37, v42
	v_mov_b32_e32 v42, v51
	v_mov_b32_e32 v50, v52
	v_mov_b32_e32 v51, v44
	v_mov_b32_e32 v44, v53
	s_waitcnt lgkmcnt(5)
	v_mov_b32_e32 v52, v70
	v_mov_b32_e32 v53, v62
	v_mov_b32_e32 v62, v71
	v_mov_b32_e32 v70, v72
	v_mov_b32_e32 v71, v64
	v_mov_b32_e32 v64, v73
	s_waitcnt lgkmcnt(1)
	v_mov_b32_e32 v72, v86
	v_mov_b32_e32 v73, v78
	v_mov_b32_e32 v78, v87
	v_mov_b32_e32 v86, v88
	v_mov_b32_e32 v87, v80
	v_mov_b32_e32 v80, v89
	v_mov_b32_e32 v88, v74
	v_mov_b32_e32 v89, v66
	v_mov_b32_e32 v66, v75
	v_mov_b32_e32 v74, v76
	v_mov_b32_e32 v75, v68
	v_mov_b32_e32 v68, v77
	s_waitcnt lgkmcnt(0)
	v_mov_b32_e32 v76, v90
	v_mov_b32_e32 v77, v82
	v_mov_b32_e32 v82, v91
	s_add_u32 s12, s12, 0xc0000
	v_mov_b32_e32 v90, v92
	v_mov_b32_e32 v91, v84
	s_addc_u32 s13, s13, 0
	s_add_i32 s33, s33, 64
	v_mov_b32_e32 v84, v93
	s_cmp_eq_u32 s12, 0xc00000
	s_waitcnt vmcnt(14)
	v_fmac_f32_e32 v3, v96, v15
	v_pk_fma_f32 v[8:9], v[96:97], v[22:23], v[8:9] op_sel_hi:[0,1,1]
	v_pk_fma_f32 v[6:7], v[96:97], v[38:39], v[6:7] op_sel_hi:[0,1,1]
	s_waitcnt vmcnt(13)
	v_pk_fma_f32 v[8:9], v[98:99], v[30:31], v[8:9] op_sel_hi:[0,1,1]
	v_pk_fma_f32 v[6:7], v[98:99], v[46:47], v[6:7] op_sel_hi:[0,1,1]
	v_fmac_f32_e32 v3, v98, v16
	s_waitcnt vmcnt(12)
	v_fmac_f32_e32 v3, v100, v17
	v_pk_fma_f32 v[8:9], v[100:101], v[24:25], v[8:9] op_sel_hi:[0,1,1]
	v_pk_fma_f32 v[6:7], v[100:101], v[40:41], v[6:7] op_sel_hi:[0,1,1]
	s_waitcnt vmcnt(11)
	v_pk_fma_f32 v[8:9], v[102:103], v[48:49], v[8:9] op_sel_hi:[0,1,1]
	v_pk_fma_f32 v[6:7], v[102:103], v[36:37], v[6:7] op_sel_hi:[0,1,1]
	v_fmac_f32_e32 v3, v102, v18
	s_waitcnt vmcnt(10)
	v_fmac_f32_e32 v3, v104, v19
	v_pk_fma_f32 v[8:9], v[104:105], v[26:27], v[8:9] op_sel_hi:[0,1,1]
	v_pk_fma_f32 v[6:7], v[104:105], v[42:43], v[6:7] op_sel_hi:[0,1,1]
	s_waitcnt vmcnt(9)
	v_pk_fma_f32 v[8:9], v[106:107], v[34:35], v[8:9] op_sel_hi:[0,1,1]
	v_pk_fma_f32 v[6:7], v[106:107], v[50:51], v[6:7] op_sel_hi:[0,1,1]
	v_fmac_f32_e32 v3, v106, v20
	s_waitcnt vmcnt(8)
	v_fmac_f32_e32 v3, v108, v21
	v_pk_fma_f32 v[8:9], v[108:109], v[28:29], v[8:9] op_sel_hi:[0,1,1]
	v_pk_fma_f32 v[6:7], v[108:109], v[44:45], v[6:7] op_sel_hi:[0,1,1]
	s_waitcnt vmcnt(7)
	v_fmac_f32_e32 v3, v110, v54
	v_pk_fma_f32 v[8:9], v[110:111], v[52:53], v[8:9] op_sel_hi:[0,1,1]
	v_pk_fma_f32 v[6:7], v[110:111], v[72:73], v[6:7] op_sel_hi:[0,1,1]
	s_waitcnt vmcnt(6)
	v_fmac_f32_e32 v3, v112, v55
	v_pk_fma_f32 v[8:9], v[112:113], v[62:63], v[8:9] op_sel_hi:[0,1,1]
	v_pk_fma_f32 v[6:7], v[112:113], v[78:79], v[6:7] op_sel_hi:[0,1,1]
	s_waitcnt vmcnt(5)
	v_fmac_f32_e32 v3, v114, v56
	v_pk_fma_f32 v[8:9], v[114:115], v[70:71], v[8:9] op_sel_hi:[0,1,1]
	v_pk_fma_f32 v[6:7], v[114:115], v[86:87], v[6:7] op_sel_hi:[0,1,1]
	s_waitcnt vmcnt(4)
	v_fmac_f32_e32 v3, v116, v57
	v_pk_fma_f32 v[8:9], v[116:117], v[64:65], v[8:9] op_sel_hi:[0,1,1]
	v_pk_fma_f32 v[6:7], v[116:117], v[80:81], v[6:7] op_sel_hi:[0,1,1]
	s_waitcnt vmcnt(3)
	v_fmac_f32_e32 v3, v118, v58
	v_pk_fma_f32 v[8:9], v[118:119], v[88:89], v[8:9] op_sel_hi:[0,1,1]
	v_pk_fma_f32 v[6:7], v[118:119], v[76:77], v[6:7] op_sel_hi:[0,1,1]
	s_waitcnt vmcnt(2)
	v_fmac_f32_e32 v3, v120, v59
	v_pk_fma_f32 v[8:9], v[120:121], v[66:67], v[8:9] op_sel_hi:[0,1,1]
	v_pk_fma_f32 v[6:7], v[120:121], v[82:83], v[6:7] op_sel_hi:[0,1,1]
	s_waitcnt vmcnt(1)
	v_fmac_f32_e32 v3, v122, v60
	v_pk_fma_f32 v[8:9], v[122:123], v[74:75], v[8:9] op_sel_hi:[0,1,1]
	v_pk_fma_f32 v[6:7], v[122:123], v[90:91], v[6:7] op_sel_hi:[0,1,1]
	s_waitcnt vmcnt(0)
	v_fmac_f32_e32 v3, v10, v61
	v_pk_fma_f32 v[8:9], v[10:11], v[68:69], v[8:9] op_sel_hi:[0,1,1]
	v_pk_fma_f32 v[6:7], v[10:11], v[84:85], v[6:7] op_sel_hi:[0,1,1]
	s_cbranch_scc0 .LBB0_104
	s_and_saveexec_b64 s[4:5], vcc
	s_cbranch_execz .LBB0_107
	v_add_u32_e32 v4, 0xa000, v12
	ds_write2_b32 v4, v3, v9 offset1:48
	ds_write2_b32 v4, v8, v7 offset0:96 offset1:144
	ds_write_b32 v12, v6 offset:41728

; __global__ void __launch_bounds__(NTHR, 2) fwd_kernel(Args a) {
;     ...
;     for (int m = gw; m < MT; m += NGW) {
;         const float* src = m < M ? a.in[I_X] + (size_t)m * DM : a.in[I_CTX] + (size_t)(m - M) * DM;
;         const float* md = mod + (m < M ? (m >> 11) : 4) * MODW;
;         f32x4 v[8]; float ss = 0.f;
; #pragma unroll
;         for (int j = 0; j < 8; ++j) { v[j] = *(const f32x4*)(src + j * 256 + lane * 4); ss += (v[j][0] * v[j][0] + v[j][1] * v[j][1]) + (v[j][2] * v[j][2] + v[j][3] * v[j][3]); }
;         const float rstd = rsqrtf(wave_sum(ss) * (1.0f / DM) + EPS);
.LBB0_163:
	global_load_dwordx4 v[48:51], v20, s[14:15] nt
	global_load_dwordx4 v[52:55], v20, s[14:15] offset:1024 nt
	global_load_dwordx4 v[56:59], v20, s[14:15] offset:2048 nt
	global_load_dwordx4 v[16:19], v20, s[14:15] offset:3072 nt
	v_lshl_add_u64 v[0:1], s[14:15], 0, v[20:21]
	v_add_co_u32_e32 v4, vcc, s20, v0
	s_min_i32 s0, s2, 0x2000
	s_nop 0
	v_addc_co_u32_e32 v5, vcc, 0, v1, vcc
	global_load_dwordx4 v[8:11], v[4:5], off nt
	global_load_dwordx4 v[12:15], v[4:5], off offset:1024 nt
	global_load_dwordx4 v[0:3], v[4:5], off offset:3072 nt
	s_nop 0
	global_load_dwordx4 v[4:7], v[4:5], off offset:2048 nt
	s_lshr_b32 s0, s0, 11
	s_mul_i32 s14, s0, 0x3000
	s_ashr_i32 s15, s14, 31
	s_lshl_b64 s[14:15], s[14:15], 2
	s_add_u32 s14, s68, s14
	s_addc_u32 s15, s69, s15
	s_add_u32 s16, s14, 0x2000
	global_load_dwordx4 v[60:63], v[22:23], off
	s_addc_u32 s17, s15, 0
	global_load_dwordx4 v[64:67], v20, s[14:15]
	global_load_dwordx4 v[68:71], v20, s[16:17]
	global_load_dwordx4 v[96:99], v[22:23], off offset:1024
	global_load_dwordx4 v[100:103], v41, s[16:17]
	global_load_dwordx4 v[104:107], v20, s[14:15] offset:1024
	global_load_dwordx4 v[108:111], v[22:23], off offset:2048
	global_load_dwordx4 v[112:115], v42, s[16:17]
	global_load_dwordx4 v[116:119], v20, s[14:15] offset:2048
	global_load_dwordx4 v[120:123], v[22:23], off offset:3072
	global_load_dwordx4 v[124:127], v43, s[16:17]
	global_load_dwordx4 v[128:131], v20, s[14:15] offset:3072
	global_load_dwordx4 v[132:135], v[24:25], off
	global_load_dwordx4 v[136:139], v44, s[16:17]
	global_load_dwordx4 v[140:143], v44, s[14:15]
	global_load_dwordx4 v[144:147], v[26:27], off
	global_load_dwordx4 v[148:151], v45, s[16:17]
	global_load_dwordx4 v[152:155], v45, s[14:15]
	global_load_dwordx4 v[156:159], v[28:29], off
	global_load_dwordx4 v[160:163], v46, s[16:17]
	global_load_dwordx4 v[164:167], v46, s[14:15]
	global_load_dwordx4 v[168:171], v[30:31], off
	global_load_dwordx4 v[172:175], v47, s[16:17]
	global_load_dwordx4 v[176:179], v47, s[14:15]
	s_lshl_b64 s[18:19], s[18:19], 12
	s_add_u32 s2, s2, s70
	s_addc_u32 s3, s3, s71
	s_add_u32 s4, s4, s12
	s_addc_u32 s5, s5, s13
	s_cmpk_gt_i32 s2, 0x23ff
	s_waitcnt vmcnt(31)
	v_mov_b32_e32 v74, v49
	s_waitcnt vmcnt(30)
	v_mov_b32_e32 v75, v53
	v_mov_b32_e32 v78, v51
	v_mov_b32_e32 v79, v55
	v_mov_b32_e32 v72, v48
	v_mov_b32_e32 v73, v52
	v_mov_b32_e32 v76, v50
	v_mov_b32_e32 v77, v54
	s_waitcnt vmcnt(29)
	v_pk_mul_f32 v[80:81], v[58:59], v[58:59]
	v_pk_mul_f32 v[82:83], v[56:57], v[56:57]
	v_pk_mul_f32 v[74:75], v[74:75], v[74:75]
	v_pk_mul_f32 v[78:79], v[78:79], v[78:79]
	v_pk_mov_b32 v[88:89], v[82:83], v[80:81] op_sel:[1,0]
	v_mov_b32_e32 v83, v81
	v_pk_fma_f32 v[72:73], v[72:73], v[72:73], v[74:75]
	v_pk_fma_f32 v[74:75], v[76:77], v[76:77], v[78:79]
	s_waitcnt vmcnt(28)
	v_mul_f32_e32 v84, v17, v17
	v_mul_f32_e32 v86, v19, v19
	v_pk_add_f32 v[76:77], v[88:89], v[82:83]
	v_pk_add_f32 v[72:73], v[72:73], v[74:75]
	v_pk_fma_f32 v[80:81], v[16:17], v[16:17], v[84:85] op_sel_hi:[1,1,0]
	v_pk_fma_f32 v[84:85], v[18:19], v[18:19], v[86:87] op_sel_hi:[1,1,0]
	s_waitcnt vmcnt(27)
	v_mul_f32_e32 v89, v8, v8
	v_mul_f32_e32 v90, v9, v9
	v_pk_add_f32 v[74:75], v[76:77], v[76:77] op_sel:[0,1] op_sel_hi:[1,0]
	v_pk_add_f32 v[72:73], v[72:73], v[72:73] op_sel:[0,1] op_sel_hi:[1,0]
	v_mul_f32_e32 v81, v10, v10
	v_mul_f32_e32 v85, v11, v11
	s_waitcnt vmcnt(26)
	v_pk_mul_f32 v[78:79], v[14:15], v[14:15]
	v_pk_mul_f32 v[82:83], v[12:13], v[12:13]
	v_mov_b32_e32 v75, v90
	v_mov_b32_e32 v73, v89
	v_pk_mov_b32 v[76:77], v[82:83], v[78:79] op_sel:[1,0]
	v_mov_b32_e32 v83, v79
	v_pk_add_f32 v[80:81], v[80:81], v[84:85]
	v_pk_add_f32 v[72:73], v[72:73], v[74:75]
	s_waitcnt vmcnt(24)
	v_mul_f32_e32 v86, v5, v5
	v_mul_f32_e32 v88, v7, v7
	v_pk_add_f32 v[76:77], v[76:77], v[82:83]
	v_pk_add_f32 v[72:73], v[72:73], v[80:81]
	v_mul_f32_e32 v91, v0, v0
	v_mul_f32_e32 v92, v1, v1
	v_mul_f32_e32 v93, v2, v2
	v_mul_f32_e32 v94, v3, v3
	v_pk_fma_f32 v[78:79], v[4:5], v[4:5], v[86:87] op_sel_hi:[1,1,0]
	v_pk_fma_f32 v[86:87], v[6:7], v[6:7], v[88:89] op_sel_hi:[1,1,0]
	v_pk_add_f32 v[76:77], v[76:77], v[76:77] op_sel:[0,1] op_sel_hi:[1,0]
	v_pk_add_f32 v[72:73], v[72:73], v[72:73] op_sel:[0,1] op_sel_hi:[1,0]
	v_mov_b32_e32 v79, v93
	v_mov_b32_e32 v87, v94
	v_mov_b32_e32 v77, v92
	v_mov_b32_e32 v73, v91
	v_pk_add_f32 v[78:79], v[78:79], v[86:87]
	v_pk_add_f32 v[72:73], v[72:73], v[76:77]
	s_waitcnt vmcnt(21)
	v_pk_add_f32 v[70:71], v[70:71], 1.0 op_sel_hi:[1,0]
	v_pk_add_f32 v[72:73], v[72:73], v[78:79]
	v_pk_add_f32 v[68:69], v[68:69], 1.0 op_sel_hi:[1,0]
	v_add_f32_e32 v72, v72, v73
	ds_bpermute_b32 v73, v34, v72
	s_waitcnt lgkmcnt(0)
	v_add_f32_e32 v72, v72, v73
	ds_bpermute_b32 v73, v35, v72
	s_waitcnt lgkmcnt(0)
	v_add_f32_e32 v72, v72, v73
	ds_bpermute_b32 v73, v36, v72
	s_waitcnt lgkmcnt(0)
	v_add_f32_e32 v72, v72, v73
	ds_bpermute_b32 v73, v37, v72
	s_waitcnt lgkmcnt(0)
	v_add_f32_e32 v72, v72, v73
	ds_bpermute_b32 v73, v38, v72
	s_waitcnt lgkmcnt(0)
	v_add_f32_e32 v72, v72, v73
	ds_bpermute_b32 v73, v39, v72
	s_waitcnt lgkmcnt(0)
; __device__ __forceinline__ void st_bf4(bf16_t* p, f32x4 v) { u32x2 w; w.x = pk2(v[0], v[1]); w.y = pk2(v[2], v[3]); *(u32x2*)p = w; }
; __global__ void __launch_bounds__(NTHR, 2) fwd_kernel(Args a) {
;     ...
;         const float rstd = rsqrtf(wave_sum(ss) * (1.0f / DM) + EPS);
; #pragma unroll
;         for (int j = 0; j < 8; ++j) { const int c = j * 256 + lane * 4;
;             const f32x4 g = *(const f32x4*)(a.in[I_G1] + c), sh = *(const f32x4*)(md + c), sc = *(const f32x4*)(md + DM + c);
;             st_bf4(H1 + (size_t)m * DM + c, (v[j] * rstd * g) * (sc + 1.0f) + sh); }
	v_add_f32_e32 v72, v72, v73
	v_fmamk_f32 v72, v72, 0x3a000000, v40
	v_mul_f32_e32 v73, 0x4b800000, v72
	v_cmp_gt_f32_e32 vcc, s21, v72
	s_nop 1
	v_cndmask_b32_e32 v72, v72, v73, vcc
	v_rsq_f32_e32 v74, v72
	v_lshl_add_u64 v[72:73], v[32:33], 0, s[18:19]
	v_mul_f32_e32 v75, 0x45800000, v74
	v_cndmask_b32_e32 v74, v74, v75, vcc
	v_pk_mul_f32 v[50:51], v[74:75], v[50:51] op_sel_hi:[0,1]
	v_pk_mul_f32 v[48:49], v[74:75], v[48:49] op_sel_hi:[0,1]
	v_pk_mul_f32 v[48:49], v[60:61], v[48:49]
	v_pk_mul_f32 v[50:51], v[62:63], v[50:51]
	v_pk_fma_f32 v[48:49], v[68:69], v[48:49], v[64:65]
	v_pk_fma_f32 v[50:51], v[70:71], v[50:51], v[66:67]
	v_cvt_pk_bf16_f32 v48, v48, v49
	v_cvt_pk_bf16_f32 v49, v50, v51
	global_store_dwordx2 v[72:73], v[48:49], off
	s_nop 0
	v_pk_mul_f32 v[54:55], v[74:75], v[54:55] op_sel_hi:[0,1]
	v_pk_mul_f32 v[52:53], v[74:75], v[52:53] op_sel_hi:[0,1]
	v_pk_mul_f32 v[58:59], v[74:75], v[58:59] op_sel_hi:[0,1]
	v_pk_mul_f32 v[56:57], v[74:75], v[56:57] op_sel_hi:[0,1]
	v_pk_mul_f32 v[18:19], v[74:75], v[18:19] op_sel_hi:[0,1]
	v_pk_mul_f32 v[16:17], v[74:75], v[16:17] op_sel_hi:[0,1]
	v_pk_mul_f32 v[10:11], v[74:75], v[10:11] op_sel_hi:[0,1]
	v_pk_mul_f32 v[8:9], v[74:75], v[8:9] op_sel_hi:[0,1]
	v_pk_mul_f32 v[14:15], v[74:75], v[14:15] op_sel_hi:[0,1]
	v_pk_mul_f32 v[12:13], v[74:75], v[12:13] op_sel_hi:[0,1]
	v_pk_mul_f32 v[6:7], v[74:75], v[6:7] op_sel_hi:[0,1]
	v_pk_mul_f32 v[4:5], v[74:75], v[4:5] op_sel_hi:[0,1]
	v_pk_mul_f32 v[2:3], v[74:75], v[2:3] op_sel_hi:[0,1]
	v_pk_mul_f32 v[0:1], v[74:75], v[0:1] op_sel_hi:[0,1]
	s_waitcnt vmcnt(21)
	v_pk_mul_f32 v[48:49], v[96:97], v[52:53]
	v_pk_mul_f32 v[50:51], v[98:99], v[54:55]
	s_waitcnt vmcnt(20)
	v_pk_add_f32 v[52:53], v[102:103], 1.0 op_sel_hi:[1,0]
	v_pk_add_f32 v[54:55], v[100:101], 1.0 op_sel_hi:[1,0]
	s_waitcnt vmcnt(19)
	v_pk_fma_f32 v[50:51], v[52:53], v[50:51], v[106:107]
	v_pk_fma_f32 v[48:49], v[54:55], v[48:49], v[104:105]
	s_nop 0
	v_cvt_pk_bf16_f32 v48, v48, v49
	v_cvt_pk_bf16_f32 v49, v50, v51
	global_store_dwordx2 v[72:73], v[48:49], off offset:512
	s_nop 0
	s_waitcnt vmcnt(19)
	v_pk_mul_f32 v[48:49], v[108:109], v[56:57]
	v_pk_mul_f32 v[50:51], v[110:111], v[58:59]
	s_waitcnt vmcnt(18)
	v_pk_add_f32 v[54:55], v[114:115], 1.0 op_sel_hi:[1,0]
	v_pk_add_f32 v[52:53], v[112:113], 1.0 op_sel_hi:[1,0]
	s_waitcnt vmcnt(17)
	v_pk_fma_f32 v[50:51], v[54:55], v[50:51], v[118:119]
	v_pk_fma_f32 v[48:49], v[52:53], v[48:49], v[116:117]
	s_nop 0
	v_cvt_pk_bf16_f32 v48, v48, v49
	v_cvt_pk_bf16_f32 v49, v50, v51
	global_store_dwordx2 v[72:73], v[48:49], off offset:1024
	s_nop 0
	s_waitcnt vmcnt(17)
	v_pk_mul_f32 v[16:17], v[120:121], v[16:17]
	v_pk_mul_f32 v[18:19], v[122:123], v[18:19]
	s_waitcnt vmcnt(16)
	v_pk_add_f32 v[48:49], v[126:127], 1.0 op_sel_hi:[1,0]
	v_pk_add_f32 v[50:51], v[124:125], 1.0 op_sel_hi:[1,0]
	s_waitcnt vmcnt(15)
	v_pk_fma_f32 v[18:19], v[48:49], v[18:19], v[130:131]
	v_pk_fma_f32 v[16:17], v[50:51], v[16:17], v[128:129]
	s_nop 0
	v_cvt_pk_bf16_f32 v16, v16, v17
	v_cvt_pk_bf16_f32 v17, v18, v19
	global_store_dwordx2 v[72:73], v[16:17], off offset:1536
	s_nop 0
	s_waitcnt vmcnt(15)
	v_pk_mul_f32 v[8:9], v[132:133], v[8:9]
	v_pk_mul_f32 v[10:11], v[134:135], v[10:11]
	s_waitcnt vmcnt(14)
	v_pk_add_f32 v[16:17], v[138:139], 1.0 op_sel_hi:[1,0]
	v_pk_add_f32 v[18:19], v[136:137], 1.0 op_sel_hi:[1,0]
	s_waitcnt vmcnt(13)
	v_pk_fma_f32 v[10:11], v[16:17], v[10:11], v[142:143]
	v_pk_fma_f32 v[8:9], v[18:19], v[8:9], v[140:141]
	s_nop 0
	v_cvt_pk_bf16_f32 v8, v8, v9
	v_cvt_pk_bf16_f32 v9, v10, v11
	global_store_dwordx2 v[72:73], v[8:9], off offset:2048
	s_nop 0
	s_waitcnt vmcnt(13)
	v_pk_mul_f32 v[8:9], v[144:145], v[12:13]
	v_pk_mul_f32 v[10:11], v[146:147], v[14:15]
	s_waitcnt vmcnt(12)
	v_pk_add_f32 v[12:13], v[150:151], 1.0 op_sel_hi:[1,0]
	v_pk_add_f32 v[14:15], v[148:149], 1.0 op_sel_hi:[1,0]
	s_waitcnt vmcnt(11)
	v_pk_fma_f32 v[10:11], v[12:13], v[10:11], v[154:155]
	v_pk_fma_f32 v[8:9], v[14:15], v[8:9], v[152:153]
	s_nop 0
	v_cvt_pk_bf16_f32 v8, v8, v9
	v_cvt_pk_bf16_f32 v9, v10, v11
	global_store_dwordx2 v[72:73], v[8:9], off offset:2560
	s_nop 0
	s_waitcnt vmcnt(11)
	v_pk_mul_f32 v[4:5], v[156:157], v[4:5]
	v_pk_mul_f32 v[6:7], v[158:159], v[6:7]
	s_waitcnt vmcnt(10)
	v_pk_add_f32 v[8:9], v[162:163], 1.0 op_sel_hi:[1,0]
	v_pk_add_f32 v[10:11], v[160:161], 1.0 op_sel_hi:[1,0]
	s_waitcnt vmcnt(9)
	v_pk_fma_f32 v[6:7], v[8:9], v[6:7], v[166:167]
	v_pk_fma_f32 v[4:5], v[10:11], v[4:5], v[164:165]
	s_nop 0
	v_cvt_pk_bf16_f32 v4, v4, v5
	v_cvt_pk_bf16_f32 v5, v6, v7
	global_store_dwordx2 v[72:73], v[4:5], off offset:3072
	s_nop 0
	s_waitcnt vmcnt(9)
	v_pk_mul_f32 v[0:1], v[168:169], v[0:1]
	v_pk_mul_f32 v[2:3], v[170:171], v[2:3]
	s_waitcnt vmcnt(8)
	v_pk_add_f32 v[4:5], v[174:175], 1.0 op_sel_hi:[1,0]
	v_pk_add_f32 v[6:7], v[172:173], 1.0 op_sel_hi:[1,0]
	s_waitcnt vmcnt(7)
	v_pk_fma_f32 v[2:3], v[4:5], v[2:3], v[178:179]
	v_pk_fma_f32 v[0:1], v[6:7], v[0:1], v[176:177]
	s_nop 0
	v_cvt_pk_bf16_f32 v0, v0, v1
	v_cvt_pk_bf16_f32 v1, v2, v3
	global_store_dwordx2 v[72:73], v[0:1], off offset:3584
	s_cbranch_scc1 .LBB0_166
